# leading half's align barrier moved from before the epilogue to inside it (after 2nd SwiGLU store / after Resid residual loads issue) so its epilogue starts during the trailing half's last MFMA block
# speedup vs baseline: 1.0033x; 1.0033x over previous
.LBB0_169:
	s_add_u32 s34, s50, 0xfff80080
	s_addc_u32 s35, s51, -1
	s_add_i32 s52, 0, 0x10000
	s_cmp_eq_u32 s77, 28
	s_cselect_b32 s55, s36, s35
	s_cselect_b32 s54, s37, s34
	v_add_u32_e32 v145, s52, v142
	s_cselect_b32 s35, s41, s76
	s_cselect_b32 s34, s43, s71
	s_add_i32 s53, 0, 0x14000
	ds_read_b128 v[146:149], v145
	ds_read_b128 v[150:153], v145 offset:1024
	ds_read_b128 v[172:175], v145 offset:2048
	ds_read_b128 v[176:179], v145 offset:3072
	v_add_u32_e32 v145, s53, v142
	ds_read_b128 v[180:183], v145
	ds_read_b128 v[184:187], v145 offset:1024
	ds_read_b128 v[188:191], v145 offset:2048
	ds_read_b128 v[192:195], v145 offset:3072
	v_lshl_add_u64 v[154:155], s[50:51], 0, v[138:139]
	s_add_i32 m0, s57, 0xc000
	ds_read_b128 v[196:199], v144
	ds_read_b128 v[200:203], v144 offset:1024
	ds_read_b128 v[204:207], v144 offset:2048
	ds_read_b128 v[208:211], v144 offset:3072
	ds_read_b128 v[212:215], v144 offset:4096
	ds_read_b128 v[216:219], v144 offset:5120
	ds_read_b128 v[228:231], v144 offset:6144
	ds_read_b128 v[232:235], v144 offset:7168
	global_load_lds_dwordx4 v[154:155], off
	v_lshl_add_u64 v[154:155], s[50:51], 0, v[140:141]
	s_add_i32 m0, s57, 0xe000
	s_nop 0
	global_load_lds_dwordx4 v[154:155], off
	s_waitcnt vmcnt(8)
	s_waitcnt lgkmcnt(0)
	s_barrier
	s_setprio 1
	v_mfma_f32_16x16x32_bf16 v[128:131], v[146:149], v[196:199], v[128:131]
	v_mfma_f32_16x16x32_bf16 v[128:131], v[150:153], v[200:203], v[128:131]
	v_mfma_f32_16x16x32_bf16 v[124:127], v[172:175], v[196:199], v[124:127]
	v_mfma_f32_16x16x32_bf16 v[124:127], v[176:179], v[200:203], v[124:127]
	v_mfma_f32_16x16x32_bf16 v[108:111], v[172:175], v[204:207], v[108:111]
	v_mfma_f32_16x16x32_bf16 v[108:111], v[176:179], v[208:211], v[108:111]
	v_mfma_f32_16x16x32_bf16 v[112:115], v[146:149], v[204:207], v[112:115]
	v_mfma_f32_16x16x32_bf16 v[112:115], v[150:153], v[208:211], v[112:115]
	v_mfma_f32_16x16x32_bf16 v[96:99], v[146:149], v[212:215], v[96:99]
	v_mfma_f32_16x16x32_bf16 v[96:99], v[150:153], v[216:219], v[96:99]
	v_mfma_f32_16x16x32_bf16 v[92:95], v[172:175], v[212:215], v[92:95]
	v_mfma_f32_16x16x32_bf16 v[92:95], v[176:179], v[216:219], v[92:95]
	v_mfma_f32_16x16x32_bf16 v[76:79], v[172:175], v[228:231], v[76:79]
	v_mfma_f32_16x16x32_bf16 v[76:79], v[176:179], v[232:235], v[76:79]
	v_mfma_f32_16x16x32_bf16 v[80:83], v[146:149], v[228:231], v[80:83]
	v_mfma_f32_16x16x32_bf16 v[80:83], v[150:153], v[232:235], v[80:83]
	v_mfma_f32_16x16x32_bf16 v[120:123], v[180:183], v[196:199], v[120:123]
	v_mfma_f32_16x16x32_bf16 v[120:123], v[184:187], v[200:203], v[120:123]
	v_mfma_f32_16x16x32_bf16 v[116:119], v[188:191], v[196:199], v[116:119]
	v_mfma_f32_16x16x32_bf16 v[116:119], v[192:195], v[200:203], v[116:119]
	v_mfma_f32_16x16x32_bf16 v[100:103], v[188:191], v[204:207], v[100:103]
	v_mfma_f32_16x16x32_bf16 v[100:103], v[192:195], v[208:211], v[100:103]
	v_mfma_f32_16x16x32_bf16 v[104:107], v[180:183], v[204:207], v[104:107]
	v_mfma_f32_16x16x32_bf16 v[104:107], v[184:187], v[208:211], v[104:107]
	v_mfma_f32_16x16x32_bf16 v[88:91], v[180:183], v[212:215], v[88:91]
	v_mfma_f32_16x16x32_bf16 v[88:91], v[184:187], v[216:219], v[88:91]
	v_mfma_f32_16x16x32_bf16 v[84:87], v[188:191], v[212:215], v[84:87]
	v_mfma_f32_16x16x32_bf16 v[84:87], v[192:195], v[216:219], v[84:87]
	v_mfma_f32_16x16x32_bf16 v[68:71], v[188:191], v[228:231], v[68:71]
	v_mfma_f32_16x16x32_bf16 v[68:71], v[192:195], v[232:235], v[68:71]
	v_mfma_f32_16x16x32_bf16 v[72:75], v[180:183], v[228:231], v[72:75]
	v_mfma_f32_16x16x32_bf16 v[72:75], v[184:187], v[232:235], v[72:75]
	s_setprio 0
	s_barrier
	s_add_i32 s52, s52, s19
	v_lshl_add_u64 v[154:155], s[34:35], 0, v[134:135]
	s_mov_b32 m0, s52
	ds_read_b128 v[196:199], v144 offset:16384
	ds_read_b128 v[200:203], v144 offset:17408
	ds_read_b128 v[204:207], v144 offset:18432
	ds_read_b128 v[208:211], v144 offset:19456
	ds_read_b128 v[212:215], v144 offset:20480
	ds_read_b128 v[216:219], v144 offset:21504
	ds_read_b128 v[228:231], v144 offset:22528
	ds_read_b128 v[232:235], v144 offset:23552
	global_load_lds_dwordx4 v[154:155], off
	s_add_i32 m0, s52, 0x2000
	s_add_u32 s96, s34, 0x4000
	v_lshl_add_u64 v[154:155], s[34:35], 0, v[0:1]
	s_addc_u32 s97, s35, 0
	s_add_i32 s52, s53, s19
	global_load_lds_dwordx4 v[154:155], off
	v_lshl_add_u64 v[154:155], s[96:97], 0, v[134:135]
	s_mov_b32 m0, s52
	v_lshl_add_u64 v[236:237], s[54:55], 0, v[132:133]
	global_load_lds_dwordx4 v[154:155], off
	v_lshl_add_u64 v[154:155], s[96:97], 0, v[0:1]
	s_add_i32 m0, s52, 0x2000
	s_nop 0
	global_load_lds_dwordx4 v[154:155], off
	v_lshl_add_u64 v[154:155], s[54:55], 0, v[136:137]
	s_mov_b32 m0, s57
	s_nop 0
	global_load_lds_dwordx4 v[154:155], off
	s_mov_b32 m0, s58
	s_nop 0
	global_load_lds_dwordx4 v[236:237], off
	s_waitcnt vmcnt(8)
	s_waitcnt lgkmcnt(0)
	s_barrier
	s_setprio 1
	v_mfma_f32_16x16x32_bf16 v[64:67], v[146:149], v[196:199], v[64:67]
	v_mfma_f32_16x16x32_bf16 v[64:67], v[150:153], v[200:203], v[64:67]
	v_mfma_f32_16x16x32_bf16 v[60:63], v[172:175], v[196:199], v[60:63]
	v_mfma_f32_16x16x32_bf16 v[60:63], v[176:179], v[200:203], v[60:63]
	v_mfma_f32_16x16x32_bf16 v[44:47], v[172:175], v[204:207], v[44:47]
	v_mfma_f32_16x16x32_bf16 v[44:47], v[176:179], v[208:211], v[44:47]
	v_mfma_f32_16x16x32_bf16 v[48:51], v[146:149], v[204:207], v[48:51]
	v_mfma_f32_16x16x32_bf16 v[48:51], v[150:153], v[208:211], v[48:51]
	v_mfma_f32_16x16x32_bf16 v[32:35], v[146:149], v[212:215], v[32:35]
	v_mfma_f32_16x16x32_bf16 v[32:35], v[150:153], v[216:219], v[32:35]
	v_mfma_f32_16x16x32_bf16 v[28:31], v[172:175], v[212:215], v[28:31]
	v_mfma_f32_16x16x32_bf16 v[28:31], v[176:179], v[216:219], v[28:31]
	v_mfma_f32_16x16x32_bf16 v[12:15], v[172:175], v[228:231], v[12:15]
	v_mfma_f32_16x16x32_bf16 v[12:15], v[176:179], v[232:235], v[12:15]
	v_mfma_f32_16x16x32_bf16 v[16:19], v[146:149], v[228:231], v[16:19]
	v_mfma_f32_16x16x32_bf16 v[16:19], v[150:153], v[232:235], v[16:19]
	v_mfma_f32_16x16x32_bf16 v[56:59], v[180:183], v[196:199], v[56:59]
	v_mfma_f32_16x16x32_bf16 v[56:59], v[184:187], v[200:203], v[56:59]
	v_mfma_f32_16x16x32_bf16 v[52:55], v[188:191], v[196:199], v[52:55]
	v_mfma_f32_16x16x32_bf16 v[52:55], v[192:195], v[200:203], v[52:55]
	v_mfma_f32_16x16x32_bf16 v[36:39], v[188:191], v[204:207], v[36:39]
	v_mfma_f32_16x16x32_bf16 v[36:39], v[192:195], v[208:211], v[36:39]
	v_mfma_f32_16x16x32_bf16 v[40:43], v[180:183], v[204:207], v[40:43]
	v_mfma_f32_16x16x32_bf16 v[40:43], v[184:187], v[208:211], v[40:43]
	v_mfma_f32_16x16x32_bf16 v[24:27], v[180:183], v[212:215], v[24:27]
	v_mfma_f32_16x16x32_bf16 v[24:27], v[184:187], v[216:219], v[24:27]
	v_mfma_f32_16x16x32_bf16 v[20:23], v[188:191], v[212:215], v[20:23]
	v_mfma_f32_16x16x32_bf16 v[20:23], v[192:195], v[216:219], v[20:23]
	v_mfma_f32_16x16x32_bf16 v[4:7], v[188:191], v[228:231], v[4:7]
	v_mfma_f32_16x16x32_bf16 v[4:7], v[192:195], v[232:235], v[4:7]
	v_mfma_f32_16x16x32_bf16 v[8:11], v[180:183], v[228:231], v[8:11]
	v_mfma_f32_16x16x32_bf16 v[8:11], v[184:187], v[232:235], v[8:11]
	s_setprio 0
	s_barrier
	s_add_i32 s52, 0, 0x18000
	v_add_u32_e32 v145, s52, v142
	s_add_i32 s53, 0, 0x1c000
	ds_read_b128 v[146:149], v145
	ds_read_b128 v[150:153], v145 offset:1024
	ds_read_b128 v[172:175], v145 offset:2048
	ds_read_b128 v[176:179], v145 offset:3072
	v_add_u32_e32 v145, s53, v142
	ds_read_b128 v[180:183], v145
	ds_read_b128 v[184:187], v145 offset:1024
	ds_read_b128 v[188:191], v145 offset:2048
	ds_read_b128 v[192:195], v145 offset:3072
	s_add_u32 s54, s54, 0x80000
	s_addc_u32 s55, s55, 0
	s_mov_b32 m0, s59
	v_lshl_add_u64 v[238:239], s[54:55], 0, v[136:137]
	ds_read_b128 v[196:199], v144 offset:32768
	ds_read_b128 v[200:203], v144 offset:33792
	ds_read_b128 v[204:207], v144 offset:34816
	ds_read_b128 v[208:211], v144 offset:35840
	ds_read_b128 v[212:215], v144 offset:36864
	ds_read_b128 v[216:219], v144 offset:37888
	ds_read_b128 v[228:231], v144 offset:38912
	ds_read_b128 v[232:235], v144 offset:39936
	global_load_lds_dwordx4 v[238:239], off
	v_lshl_add_u64 v[238:239], s[54:55], 0, v[132:133]
	s_mov_b32 m0, s60
	s_nop 0
	global_load_lds_dwordx4 v[238:239], off
	s_waitcnt vmcnt(8)
	s_waitcnt lgkmcnt(0)
	s_barrier
	s_setprio 1
	v_mfma_f32_16x16x32_bf16 v[128:131], v[146:149], v[196:199], v[128:131]
	v_mfma_f32_16x16x32_bf16 v[128:131], v[150:153], v[200:203], v[128:131]
	v_mfma_f32_16x16x32_bf16 v[124:127], v[172:175], v[196:199], v[124:127]
	v_mfma_f32_16x16x32_bf16 v[124:127], v[176:179], v[200:203], v[124:127]
	v_mfma_f32_16x16x32_bf16 v[108:111], v[172:175], v[204:207], v[108:111]
	v_mfma_f32_16x16x32_bf16 v[108:111], v[176:179], v[208:211], v[108:111]
	v_mfma_f32_16x16x32_bf16 v[112:115], v[146:149], v[204:207], v[112:115]
	v_mfma_f32_16x16x32_bf16 v[112:115], v[150:153], v[208:211], v[112:115]
	v_mfma_f32_16x16x32_bf16 v[96:99], v[146:149], v[212:215], v[96:99]
	v_mfma_f32_16x16x32_bf16 v[96:99], v[150:153], v[216:219], v[96:99]
	v_mfma_f32_16x16x32_bf16 v[92:95], v[172:175], v[212:215], v[92:95]
	v_mfma_f32_16x16x32_bf16 v[92:95], v[176:179], v[216:219], v[92:95]
	v_mfma_f32_16x16x32_bf16 v[76:79], v[172:175], v[228:231], v[76:79]
	v_mfma_f32_16x16x32_bf16 v[76:79], v[176:179], v[232:235], v[76:79]
	v_mfma_f32_16x16x32_bf16 v[80:83], v[146:149], v[228:231], v[80:83]
	v_mfma_f32_16x16x32_bf16 v[80:83], v[150:153], v[232:235], v[80:83]
	v_mfma_f32_16x16x32_bf16 v[120:123], v[180:183], v[196:199], v[120:123]
	v_mfma_f32_16x16x32_bf16 v[120:123], v[184:187], v[200:203], v[120:123]
	v_mfma_f32_16x16x32_bf16 v[116:119], v[188:191], v[196:199], v[116:119]
	v_mfma_f32_16x16x32_bf16 v[116:119], v[192:195], v[200:203], v[116:119]
	v_mfma_f32_16x16x32_bf16 v[100:103], v[188:191], v[204:207], v[100:103]
	v_mfma_f32_16x16x32_bf16 v[100:103], v[192:195], v[208:211], v[100:103]
	v_mfma_f32_16x16x32_bf16 v[104:107], v[180:183], v[204:207], v[104:107]
	v_mfma_f32_16x16x32_bf16 v[104:107], v[184:187], v[208:211], v[104:107]
	v_mfma_f32_16x16x32_bf16 v[88:91], v[180:183], v[212:215], v[88:91]
	v_mfma_f32_16x16x32_bf16 v[88:91], v[184:187], v[216:219], v[88:91]
	v_mfma_f32_16x16x32_bf16 v[84:87], v[188:191], v[212:215], v[84:87]
	v_mfma_f32_16x16x32_bf16 v[84:87], v[192:195], v[216:219], v[84:87]
	v_mfma_f32_16x16x32_bf16 v[68:71], v[188:191], v[228:231], v[68:71]
	v_mfma_f32_16x16x32_bf16 v[68:71], v[192:195], v[232:235], v[68:71]
	v_mfma_f32_16x16x32_bf16 v[72:75], v[180:183], v[228:231], v[72:75]
	v_mfma_f32_16x16x32_bf16 v[72:75], v[184:187], v[232:235], v[72:75]
	s_setprio 0
	s_barrier
	s_add_u32 s54, s34, 0x160000
	s_addc_u32 s55, s35, 0
	s_add_i32 s52, s52, s19
	v_lshl_add_u64 v[238:239], s[54:55], 0, v[134:135]
	s_mov_b32 m0, s52
	ds_read_b128 v[196:199], v144 offset:49152
	ds_read_b128 v[200:203], v144 offset:50176
	ds_read_b128 v[204:207], v144 offset:51200
	ds_read_b128 v[208:211], v144 offset:52224
	ds_read_b128 v[212:215], v144 offset:53248
	ds_read_b128 v[216:219], v144 offset:54272
	ds_read_b128 v[228:231], v144 offset:55296
	ds_read_b128 v[232:235], v144 offset:56320
	global_load_lds_dwordx4 v[238:239], off
	s_add_i32 m0, s52, 0x2000
	s_add_u32 s34, s34, 0x164000
	v_lshl_add_u64 v[238:239], s[54:55], 0, v[0:1]
	s_addc_u32 s35, s35, 0
	s_add_i32 s52, s53, s19
	global_load_lds_dwordx4 v[238:239], off
	v_lshl_add_u64 v[238:239], s[34:35], 0, v[134:135]
	s_mov_b32 m0, s52
	v_lshl_add_u64 v[154:155], v[154:155], 0, s[14:15]
	global_load_lds_dwordx4 v[238:239], off
	v_lshl_add_u64 v[238:239], s[34:35], 0, v[0:1]
	s_add_i32 m0, s52, 0x2000
	s_nop 0
	global_load_lds_dwordx4 v[238:239], off
	s_mov_b32 m0, s61
	s_nop 0
	global_load_lds_dwordx4 v[154:155], off
	v_lshl_add_u64 v[154:155], v[236:237], 0, s[14:15]
	s_mov_b32 m0, s62
	s_nop 0
	global_load_lds_dwordx4 v[154:155], off
	s_waitcnt vmcnt(8)
	s_waitcnt lgkmcnt(0)
	s_barrier
	s_setprio 1
	v_mfma_f32_16x16x32_bf16 v[64:67], v[146:149], v[196:199], v[64:67]
	v_mfma_f32_16x16x32_bf16 v[64:67], v[150:153], v[200:203], v[64:67]
	v_mfma_f32_16x16x32_bf16 v[60:63], v[172:175], v[196:199], v[60:63]
	v_mfma_f32_16x16x32_bf16 v[60:63], v[176:179], v[200:203], v[60:63]
	v_mfma_f32_16x16x32_bf16 v[44:47], v[172:175], v[204:207], v[44:47]
	v_mfma_f32_16x16x32_bf16 v[44:47], v[176:179], v[208:211], v[44:47]
	v_mfma_f32_16x16x32_bf16 v[48:51], v[146:149], v[204:207], v[48:51]
	v_mfma_f32_16x16x32_bf16 v[48:51], v[150:153], v[208:211], v[48:51]
	v_mfma_f32_16x16x32_bf16 v[32:35], v[146:149], v[212:215], v[32:35]
	v_mfma_f32_16x16x32_bf16 v[32:35], v[150:153], v[216:219], v[32:35]
	v_mfma_f32_16x16x32_bf16 v[28:31], v[172:175], v[212:215], v[28:31]
	v_mfma_f32_16x16x32_bf16 v[28:31], v[176:179], v[216:219], v[28:31]
	v_mfma_f32_16x16x32_bf16 v[12:15], v[172:175], v[228:231], v[12:15]
	v_mfma_f32_16x16x32_bf16 v[12:15], v[176:179], v[232:235], v[12:15]
	v_mfma_f32_16x16x32_bf16 v[16:19], v[146:149], v[228:231], v[16:19]
	v_mfma_f32_16x16x32_bf16 v[16:19], v[150:153], v[232:235], v[16:19]
	v_mfma_f32_16x16x32_bf16 v[56:59], v[180:183], v[196:199], v[56:59]
	v_mfma_f32_16x16x32_bf16 v[56:59], v[184:187], v[200:203], v[56:59]
	v_mfma_f32_16x16x32_bf16 v[52:55], v[188:191], v[196:199], v[52:55]
	v_mfma_f32_16x16x32_bf16 v[52:55], v[192:195], v[200:203], v[52:55]
	v_mfma_f32_16x16x32_bf16 v[36:39], v[188:191], v[204:207], v[36:39]
	v_mfma_f32_16x16x32_bf16 v[36:39], v[192:195], v[208:211], v[36:39]
	v_mfma_f32_16x16x32_bf16 v[40:43], v[180:183], v[204:207], v[40:43]
	v_mfma_f32_16x16x32_bf16 v[40:43], v[184:187], v[208:211], v[40:43]
	v_mfma_f32_16x16x32_bf16 v[24:27], v[180:183], v[212:215], v[24:27]
	v_mfma_f32_16x16x32_bf16 v[24:27], v[184:187], v[216:219], v[24:27]
	v_mfma_f32_16x16x32_bf16 v[20:23], v[188:191], v[212:215], v[20:23]
	v_mfma_f32_16x16x32_bf16 v[20:23], v[192:195], v[216:219], v[20:23]
	v_mfma_f32_16x16x32_bf16 v[4:7], v[188:191], v[228:231], v[4:7]
	v_mfma_f32_16x16x32_bf16 v[4:7], v[192:195], v[232:235], v[4:7]
	v_mfma_f32_16x16x32_bf16 v[8:11], v[180:183], v[228:231], v[8:11]
	v_mfma_f32_16x16x32_bf16 v[8:11], v[184:187], v[232:235], v[8:11]
	s_setprio 0
	s_barrier
	s_add_i32 s77, s77, 2
	s_add_u32 s71, s71, 0x2c0000
	s_addc_u32 s76, s76, 0
	s_add_u32 s50, s50, 0x100
	s_addc_u32 s51, s51, 0
	s_cmp_gt_u32 s77, 29
	s_cbranch_scc0 .LBB0_169
	s_and_b64 vcc, exec, s[28:29]
	s_cbranch_vccz .LBB0_172
	s_nop 0
.LBB0_172:
	v_lshl_add_u32 v153, s69, 8, v3
	v_and_b32_e32 v145, 0x7cf, v153
	v_lshl_add_u32 v147, v145, 2, s92
	v_bitop3_b32 v145, v153, s5, 16 bitop3:0xc8
	v_lshl_add_u32 v149, v145, 2, s92
	v_bitop3_b32 v145, v153, s8, 32 bitop3:0xc8
	v_lshl_add_u32 v150, v145, 2, s92
	v_bitop3_b32 v145, v153, s9, 48 bitop3:0xc8
	v_add_u32_e32 v176, 0x80, v153
	v_lshl_add_u32 v151, v145, 2, s92
	v_and_b32_e32 v145, 0x7cf, v176
	v_add_u32_e32 v148, 0x90, v153
	v_lshl_add_u32 v152, v145, 2, s92
	v_and_b32_e32 v145, 0x7df, v148
	v_add_u32_e32 v146, 0xa0, v153
	v_lshl_add_u32 v154, v145, 2, s92
	v_and_b32_e32 v145, 0x7ef, v146
	v_lshl_add_u32 v172, v145, 2, s92
	v_add_u32_e32 v145, 0xb0, v153
	v_and_b32_e32 v173, 0x7ff, v145
	v_lshl_add_u32 v173, v173, 2, s92
	ds_read_b32 v177, v147
	ds_read_b32 v178, v149
	ds_read_b32 v179, v150
	ds_read_b32 v180, v151
	ds_read_b32 v181, v152
	ds_read_b32 v182, v154
	ds_read_b32 v149, v172
	ds_read_b32 v147, v173
	s_waitcnt lgkmcnt(0)
	v_mul_f32_e32 v152, 0xbfb8aa3b, v177
	v_pk_mul_f32 v[172:173], v[128:129], v[152:153] op_sel_hi:[1,0]
	v_pk_mul_f32 v[122:123], v[130:131], v[122:123]
	v_pk_mul_f32 v[120:121], v[128:129], v[120:121]
	v_exp_f32_e32 v128, v172
	v_exp_f32_e32 v129, v173
	v_pk_mul_f32 v[130:131], v[130:131], v[152:153] op_sel_hi:[1,0]
	v_pk_mul_f32 v[172:173], v[124:125], v[152:153] op_sel_hi:[1,0]
	v_exp_f32_e32 v130, v130
	v_exp_f32_e32 v131, v131
	v_pk_mul_f32 v[118:119], v[126:127], v[118:119]
	v_pk_mul_f32 v[116:117], v[124:125], v[116:117]
	v_exp_f32_e32 v124, v172
	v_exp_f32_e32 v125, v173
	v_pk_mul_f32 v[126:127], v[126:127], v[152:153] op_sel_hi:[1,0]
	v_pk_add_f32 v[128:129], v[128:129], 1.0 op_sel_hi:[1,0]
	v_exp_f32_e32 v126, v126
	v_exp_f32_e32 v127, v127
	v_pk_add_f32 v[130:131], v[130:131], 1.0 op_sel_hi:[1,0]
	v_pk_add_f32 v[124:125], v[124:125], 1.0 op_sel_hi:[1,0]
	v_rcp_f32_e32 v128, v128
	v_rcp_f32_e32 v129, v129
	v_rcp_f32_e32 v130, v130
	v_rcp_f32_e32 v131, v131
	v_rcp_f32_e32 v124, v124
	v_rcp_f32_e32 v125, v125
	v_pk_add_f32 v[126:127], v[126:127], 1.0 op_sel_hi:[1,0]
	v_or_b32_e32 v155, 16, v153
	v_rcp_f32_e32 v126, v126
	v_rcp_f32_e32 v127, v127
	v_mul_f32_e32 v154, v177, v177
	v_pk_mul_f32 v[120:121], v[120:121], v[154:155] op_sel_hi:[1,0]
	v_pk_mul_f32 v[122:123], v[122:123], v[154:155] op_sel_hi:[1,0]
	v_pk_mul_f32 v[116:117], v[116:117], v[154:155] op_sel_hi:[1,0]
	v_lshl_or_b32 v150, s64, 7, v143
	v_pk_mul_f32 v[118:119], v[118:119], v[154:155] op_sel_hi:[1,0]
	v_pk_mul_f32 v[120:121], v[120:121], v[128:129]
	v_pk_mul_f32 v[122:123], v[122:123], v[130:131]
	v_pk_mul_f32 v[116:117], v[116:117], v[124:125]
	v_ashrrev_i32_e32 v151, 31, v150
	v_pk_mul_f32 v[118:119], v[118:119], v[126:127]
	v_cvt_pk_bf16_f32 v120, v120, v121
	v_cvt_pk_bf16_f32 v121, v122, v123
	v_cvt_pk_bf16_f32 v122, v116, v117
	v_mov_b64_e32 v[116:117], s[22:23]
	v_cvt_pk_bf16_f32 v123, v118, v119
	v_mad_i64_i32 v[124:125], s[34:35], v153, s11, v[116:117]
	v_lshlrev_b64 v[118:119], 1, v[150:151]
	v_lshl_add_u64 v[124:125], v[124:125], 0, v[118:119]
	global_store_dwordx4 v[124:125], v[120:123], off
	v_pk_mul_f32 v[104:105], v[112:113], v[104:105]
	v_pk_mul_f32 v[100:101], v[108:109], v[100:101]
	v_mul_f32_e32 v120, 0xbfb8aa3b, v178
	v_pk_mul_f32 v[124:125], v[112:113], v[120:121] op_sel_hi:[1,0]
	v_pk_mul_f32 v[106:107], v[114:115], v[106:107]
	v_exp_f32_e32 v112, v124
	v_exp_f32_e32 v113, v125
	v_pk_mul_f32 v[124:125], v[108:109], v[120:121] op_sel_hi:[1,0]
	v_pk_mul_f32 v[114:115], v[114:115], v[120:121] op_sel_hi:[1,0]
	v_exp_f32_e32 v108, v124
	v_exp_f32_e32 v109, v125
	v_pk_mul_f32 v[102:103], v[110:111], v[102:103]
	v_pk_mul_f32 v[110:111], v[110:111], v[120:121] op_sel_hi:[1,0]
	v_exp_f32_e32 v114, v114
	v_exp_f32_e32 v115, v115
	v_exp_f32_e32 v110, v110
	v_exp_f32_e32 v111, v111
	v_pk_add_f32 v[112:113], v[112:113], 1.0 op_sel_hi:[1,0]
	v_pk_add_f32 v[108:109], v[108:109], 1.0 op_sel_hi:[1,0]
	v_rcp_f32_e32 v112, v112
	v_rcp_f32_e32 v113, v113
	v_rcp_f32_e32 v108, v108
	v_rcp_f32_e32 v109, v109
	v_mul_f32_e32 v122, v178, v178
	v_pk_add_f32 v[114:115], v[114:115], 1.0 op_sel_hi:[1,0]
	v_pk_add_f32 v[110:111], v[110:111], 1.0 op_sel_hi:[1,0]
	v_pk_mul_f32 v[104:105], v[104:105], v[122:123] op_sel_hi:[1,0]
	v_rcp_f32_e32 v114, v114
	v_rcp_f32_e32 v115, v115
	v_rcp_f32_e32 v110, v110
	v_rcp_f32_e32 v111, v111
	v_pk_mul_f32 v[100:101], v[100:101], v[122:123] op_sel_hi:[1,0]
	v_pk_mul_f32 v[104:105], v[104:105], v[112:113]
	v_pk_mul_f32 v[108:109], v[100:101], v[108:109]
	v_cvt_pk_bf16_f32 v100, v104, v105
	v_mad_i64_i32 v[104:105], s[34:35], v155, s11, v[116:117]
	v_pk_mul_f32 v[106:107], v[106:107], v[122:123] op_sel_hi:[1,0]
	v_pk_mul_f32 v[102:103], v[102:103], v[122:123] op_sel_hi:[1,0]
	v_lshl_add_u64 v[104:105], v[104:105], 0, v[118:119]
	v_pk_mul_f32 v[106:107], v[106:107], v[114:115]
	v_pk_mul_f32 v[110:111], v[102:103], v[110:111]
	v_cvt_pk_bf16_f32 v101, v106, v107
	v_cvt_pk_bf16_f32 v102, v108, v109
	v_pk_mul_f32 v[88:89], v[96:97], v[88:89]
	v_cvt_pk_bf16_f32 v103, v110, v111
	global_store_dwordx4 v[104:105], v[100:103], off
	s_and_b64 vcc, exec, s[28:29]
	s_cbranch_vccz .Lmidbar_1
	s_barrier
.Lmidbar_1:
	v_pk_mul_f32 v[84:85], v[92:93], v[84:85]
	v_pk_mul_f32 v[90:91], v[98:99], v[90:91]
	v_mul_f32_e32 v100, 0xbfb8aa3b, v179
	v_pk_mul_f32 v[104:105], v[96:97], v[100:101] op_sel_hi:[1,0]
	v_pk_mul_f32 v[98:99], v[98:99], v[100:101] op_sel_hi:[1,0]
	v_exp_f32_e32 v96, v104
	v_exp_f32_e32 v97, v105
	v_pk_mul_f32 v[104:105], v[92:93], v[100:101] op_sel_hi:[1,0]
	v_pk_mul_f32 v[86:87], v[94:95], v[86:87]
	v_exp_f32_e32 v92, v104
	v_exp_f32_e32 v93, v105
	v_pk_mul_f32 v[94:95], v[94:95], v[100:101] op_sel_hi:[1,0]
	v_exp_f32_e32 v98, v98
	v_exp_f32_e32 v99, v99
	v_exp_f32_e32 v94, v94
	v_exp_f32_e32 v95, v95
	v_pk_add_f32 v[96:97], v[96:97], 1.0 op_sel_hi:[1,0]
	v_pk_add_f32 v[92:93], v[92:93], 1.0 op_sel_hi:[1,0]
	v_rcp_f32_e32 v96, v96
	v_rcp_f32_e32 v97, v97
	v_rcp_f32_e32 v92, v92
	v_rcp_f32_e32 v93, v93
	v_mul_f32_e32 v102, v179, v179
	v_pk_add_f32 v[98:99], v[98:99], 1.0 op_sel_hi:[1,0]
	v_pk_add_f32 v[94:95], v[94:95], 1.0 op_sel_hi:[1,0]
	v_pk_mul_f32 v[88:89], v[88:89], v[102:103] op_sel_hi:[1,0]
	v_rcp_f32_e32 v98, v98
	v_rcp_f32_e32 v99, v99
	v_rcp_f32_e32 v94, v94
	v_rcp_f32_e32 v95, v95
	v_or_b32_e32 v174, 32, v153
	v_pk_mul_f32 v[84:85], v[84:85], v[102:103] op_sel_hi:[1,0]
	v_pk_mul_f32 v[88:89], v[88:89], v[96:97]
	v_pk_mul_f32 v[92:93], v[84:85], v[92:93]
	v_cvt_pk_bf16_f32 v84, v88, v89
	v_mad_i64_i32 v[88:89], s[34:35], v174, s11, v[116:117]
	v_pk_mul_f32 v[90:91], v[90:91], v[102:103] op_sel_hi:[1,0]
	v_pk_mul_f32 v[86:87], v[86:87], v[102:103] op_sel_hi:[1,0]
	v_lshl_add_u64 v[88:89], v[88:89], 0, v[118:119]
	v_pk_mul_f32 v[90:91], v[90:91], v[98:99]
	v_pk_mul_f32 v[94:95], v[86:87], v[94:95]
	v_cvt_pk_bf16_f32 v85, v90, v91
	v_cvt_pk_bf16_f32 v86, v92, v93
	v_pk_mul_f32 v[72:73], v[80:81], v[72:73]
	v_cvt_pk_bf16_f32 v87, v94, v95
	global_store_dwordx4 v[88:89], v[84:87], off
	v_pk_mul_f32 v[68:69], v[76:77], v[68:69]
	v_pk_mul_f32 v[74:75], v[82:83], v[74:75]
	v_mul_f32_e32 v84, 0xbfb8aa3b, v180
	v_pk_mul_f32 v[88:89], v[80:81], v[84:85] op_sel_hi:[1,0]
	v_pk_mul_f32 v[82:83], v[82:83], v[84:85] op_sel_hi:[1,0]
	v_exp_f32_e32 v80, v88
	v_exp_f32_e32 v81, v89
	v_pk_mul_f32 v[88:89], v[76:77], v[84:85] op_sel_hi:[1,0]
	v_pk_mul_f32 v[70:71], v[78:79], v[70:71]
	v_exp_f32_e32 v76, v88
	v_exp_f32_e32 v77, v89
	v_pk_mul_f32 v[78:79], v[78:79], v[84:85] op_sel_hi:[1,0]
	v_exp_f32_e32 v82, v82
	v_exp_f32_e32 v83, v83
	v_exp_f32_e32 v78, v78
	v_exp_f32_e32 v79, v79
	v_pk_add_f32 v[80:81], v[80:81], 1.0 op_sel_hi:[1,0]
	v_pk_add_f32 v[76:77], v[76:77], 1.0 op_sel_hi:[1,0]
	v_rcp_f32_e32 v80, v80
	v_rcp_f32_e32 v81, v81
	v_rcp_f32_e32 v76, v76
	v_rcp_f32_e32 v77, v77
	v_mul_f32_e32 v86, v180, v180
	v_pk_add_f32 v[82:83], v[82:83], 1.0 op_sel_hi:[1,0]
	v_pk_add_f32 v[78:79], v[78:79], 1.0 op_sel_hi:[1,0]
	v_pk_mul_f32 v[72:73], v[72:73], v[86:87] op_sel_hi:[1,0]
	v_rcp_f32_e32 v82, v82
	v_rcp_f32_e32 v83, v83
	v_rcp_f32_e32 v78, v78
	v_rcp_f32_e32 v79, v79
	v_or_b32_e32 v175, 48, v153
	v_pk_mul_f32 v[68:69], v[68:69], v[86:87] op_sel_hi:[1,0]
	v_pk_mul_f32 v[72:73], v[72:73], v[80:81]
	v_pk_mul_f32 v[76:77], v[68:69], v[76:77]
	v_cvt_pk_bf16_f32 v68, v72, v73
	v_mad_i64_i32 v[72:73], s[34:35], v175, s11, v[116:117]
	v_pk_mul_f32 v[74:75], v[74:75], v[86:87] op_sel_hi:[1,0]
	v_pk_mul_f32 v[70:71], v[70:71], v[86:87] op_sel_hi:[1,0]
	v_lshl_add_u64 v[72:73], v[72:73], 0, v[118:119]
	v_pk_mul_f32 v[74:75], v[74:75], v[82:83]
	v_pk_mul_f32 v[78:79], v[70:71], v[78:79]
	v_cvt_pk_bf16_f32 v69, v74, v75
	v_cvt_pk_bf16_f32 v70, v76, v77
	v_pk_mul_f32 v[56:57], v[64:65], v[56:57]
	v_cvt_pk_bf16_f32 v71, v78, v79
	global_store_dwordx4 v[72:73], v[68:71], off
	v_pk_mul_f32 v[52:53], v[60:61], v[52:53]
	v_pk_mul_f32 v[58:59], v[66:67], v[58:59]
	v_mul_f32_e32 v68, 0xbfb8aa3b, v181
	v_pk_mul_f32 v[72:73], v[64:65], v[68:69] op_sel_hi:[1,0]
	v_pk_mul_f32 v[66:67], v[66:67], v[68:69] op_sel_hi:[1,0]
	v_exp_f32_e32 v64, v72
	v_exp_f32_e32 v65, v73
	v_pk_mul_f32 v[72:73], v[60:61], v[68:69] op_sel_hi:[1,0]
	v_pk_mul_f32 v[54:55], v[62:63], v[54:55]
	v_exp_f32_e32 v60, v72
	v_exp_f32_e32 v61, v73
	v_pk_mul_f32 v[62:63], v[62:63], v[68:69] op_sel_hi:[1,0]
	v_exp_f32_e32 v66, v66
	v_exp_f32_e32 v67, v67
	v_exp_f32_e32 v62, v62
	v_exp_f32_e32 v63, v63
	v_pk_add_f32 v[64:65], v[64:65], 1.0 op_sel_hi:[1,0]
	v_pk_add_f32 v[60:61], v[60:61], 1.0 op_sel_hi:[1,0]
	v_rcp_f32_e32 v64, v64
	v_rcp_f32_e32 v65, v65
	v_rcp_f32_e32 v60, v60
	v_rcp_f32_e32 v61, v61
	v_mul_f32_e32 v70, v181, v181
	v_pk_add_f32 v[66:67], v[66:67], 1.0 op_sel_hi:[1,0]
	v_pk_add_f32 v[62:63], v[62:63], 1.0 op_sel_hi:[1,0]
	v_pk_mul_f32 v[56:57], v[56:57], v[70:71] op_sel_hi:[1,0]
	v_rcp_f32_e32 v66, v66
	v_rcp_f32_e32 v67, v67
	v_rcp_f32_e32 v62, v62
	v_rcp_f32_e32 v63, v63
	v_pk_mul_f32 v[52:53], v[52:53], v[70:71] op_sel_hi:[1,0]
	v_pk_mul_f32 v[56:57], v[56:57], v[64:65]
	v_pk_mul_f32 v[60:61], v[52:53], v[60:61]
	v_cvt_pk_bf16_f32 v52, v56, v57
	v_mad_i64_i32 v[56:57], s[34:35], v176, s11, v[116:117]
	v_pk_mul_f32 v[58:59], v[58:59], v[70:71] op_sel_hi:[1,0]
	v_pk_mul_f32 v[54:55], v[54:55], v[70:71] op_sel_hi:[1,0]
	v_lshl_add_u64 v[56:57], v[56:57], 0, v[118:119]
	v_pk_mul_f32 v[58:59], v[58:59], v[66:67]
	v_pk_mul_f32 v[62:63], v[54:55], v[62:63]
	v_cvt_pk_bf16_f32 v53, v58, v59
	v_cvt_pk_bf16_f32 v54, v60, v61
	v_pk_mul_f32 v[40:41], v[48:49], v[40:41]
	v_cvt_pk_bf16_f32 v55, v62, v63
	global_store_dwordx4 v[56:57], v[52:55], off
	v_pk_mul_f32 v[36:37], v[44:45], v[36:37]
	v_pk_mul_f32 v[42:43], v[50:51], v[42:43]
	v_mul_f32_e32 v52, 0xbfb8aa3b, v182
	v_pk_mul_f32 v[56:57], v[48:49], v[52:53] op_sel_hi:[1,0]
	v_pk_mul_f32 v[50:51], v[50:51], v[52:53] op_sel_hi:[1,0]
	v_exp_f32_e32 v48, v56
	v_exp_f32_e32 v49, v57
	v_pk_mul_f32 v[56:57], v[44:45], v[52:53] op_sel_hi:[1,0]
	v_pk_mul_f32 v[38:39], v[46:47], v[38:39]
	v_exp_f32_e32 v44, v56
	v_exp_f32_e32 v45, v57
	v_pk_mul_f32 v[46:47], v[46:47], v[52:53] op_sel_hi:[1,0]
	v_exp_f32_e32 v50, v50
	v_exp_f32_e32 v51, v51
	v_exp_f32_e32 v46, v46
	v_exp_f32_e32 v47, v47
	v_pk_add_f32 v[48:49], v[48:49], 1.0 op_sel_hi:[1,0]
	v_pk_add_f32 v[44:45], v[44:45], 1.0 op_sel_hi:[1,0]
	v_rcp_f32_e32 v48, v48
	v_rcp_f32_e32 v49, v49
	v_rcp_f32_e32 v44, v44
	v_rcp_f32_e32 v45, v45
	v_mul_f32_e32 v54, v182, v182
	v_pk_add_f32 v[50:51], v[50:51], 1.0 op_sel_hi:[1,0]
	v_pk_add_f32 v[46:47], v[46:47], 1.0 op_sel_hi:[1,0]
	v_pk_mul_f32 v[40:41], v[40:41], v[54:55] op_sel_hi:[1,0]
	v_rcp_f32_e32 v50, v50
	v_rcp_f32_e32 v51, v51
	v_rcp_f32_e32 v46, v46
	v_rcp_f32_e32 v47, v47
	v_pk_mul_f32 v[36:37], v[36:37], v[54:55] op_sel_hi:[1,0]
	v_pk_mul_f32 v[40:41], v[40:41], v[48:49]
	v_pk_mul_f32 v[44:45], v[36:37], v[44:45]
	v_cvt_pk_bf16_f32 v36, v40, v41
	v_mad_i64_i32 v[40:41], s[34:35], v148, s11, v[116:117]
	v_pk_mul_f32 v[42:43], v[42:43], v[54:55] op_sel_hi:[1,0]
	v_pk_mul_f32 v[38:39], v[38:39], v[54:55] op_sel_hi:[1,0]
	v_lshl_add_u64 v[40:41], v[40:41], 0, v[118:119]
	v_pk_mul_f32 v[42:43], v[42:43], v[50:51]
	v_pk_mul_f32 v[46:47], v[38:39], v[46:47]
	v_cvt_pk_bf16_f32 v37, v42, v43
	v_cvt_pk_bf16_f32 v38, v44, v45
	v_pk_mul_f32 v[24:25], v[32:33], v[24:25]
	v_cvt_pk_bf16_f32 v39, v46, v47
	global_store_dwordx4 v[40:41], v[36:39], off
	v_pk_mul_f32 v[20:21], v[28:29], v[20:21]
	v_pk_mul_f32 v[26:27], v[34:35], v[26:27]
	v_mul_f32_e32 v36, 0xbfb8aa3b, v149
	v_pk_mul_f32 v[40:41], v[32:33], v[36:37] op_sel_hi:[1,0]
	v_pk_mul_f32 v[34:35], v[34:35], v[36:37] op_sel_hi:[1,0]
	v_exp_f32_e32 v32, v40
	v_exp_f32_e32 v33, v41
	v_pk_mul_f32 v[40:41], v[28:29], v[36:37] op_sel_hi:[1,0]
	v_pk_mul_f32 v[22:23], v[30:31], v[22:23]
	v_exp_f32_e32 v28, v40
	v_exp_f32_e32 v29, v41
	v_pk_mul_f32 v[30:31], v[30:31], v[36:37] op_sel_hi:[1,0]
	v_exp_f32_e32 v34, v34
	v_exp_f32_e32 v35, v35
	v_exp_f32_e32 v30, v30
	v_exp_f32_e32 v31, v31
	v_pk_add_f32 v[32:33], v[32:33], 1.0 op_sel_hi:[1,0]
	v_pk_add_f32 v[28:29], v[28:29], 1.0 op_sel_hi:[1,0]
	v_rcp_f32_e32 v32, v32
	v_rcp_f32_e32 v33, v33
	v_rcp_f32_e32 v28, v28
	v_rcp_f32_e32 v29, v29
	v_mul_f32_e32 v38, v149, v149
	v_pk_add_f32 v[34:35], v[34:35], 1.0 op_sel_hi:[1,0]
	v_pk_add_f32 v[30:31], v[30:31], 1.0 op_sel_hi:[1,0]
	v_pk_mul_f32 v[24:25], v[24:25], v[38:39] op_sel_hi:[1,0]
	v_rcp_f32_e32 v34, v34
	v_rcp_f32_e32 v35, v35
	v_rcp_f32_e32 v30, v30
	v_rcp_f32_e32 v31, v31
	v_pk_mul_f32 v[20:21], v[20:21], v[38:39] op_sel_hi:[1,0]
	v_pk_mul_f32 v[24:25], v[24:25], v[32:33]
	v_pk_mul_f32 v[28:29], v[20:21], v[28:29]
	v_cvt_pk_bf16_f32 v20, v24, v25
	v_mad_i64_i32 v[24:25], s[34:35], v146, s11, v[116:117]
	v_pk_mul_f32 v[26:27], v[26:27], v[38:39] op_sel_hi:[1,0]
	v_pk_mul_f32 v[22:23], v[22:23], v[38:39] op_sel_hi:[1,0]
	v_lshl_add_u64 v[24:25], v[24:25], 0, v[118:119]
	v_pk_mul_f32 v[26:27], v[26:27], v[34:35]
	v_pk_mul_f32 v[30:31], v[22:23], v[30:31]
	v_cvt_pk_bf16_f32 v21, v26, v27
	v_cvt_pk_bf16_f32 v22, v28, v29
	v_pk_mul_f32 v[8:9], v[16:17], v[8:9]
	v_cvt_pk_bf16_f32 v23, v30, v31
	global_store_dwordx4 v[24:25], v[20:23], off
	v_pk_mul_f32 v[4:5], v[12:13], v[4:5]
	v_pk_mul_f32 v[10:11], v[18:19], v[10:11]
	v_mul_f32_e32 v20, 0xbfb8aa3b, v147
	v_pk_mul_f32 v[24:25], v[16:17], v[20:21] op_sel_hi:[1,0]
	v_pk_mul_f32 v[18:19], v[18:19], v[20:21] op_sel_hi:[1,0]
	v_exp_f32_e32 v16, v24
	v_exp_f32_e32 v17, v25
	v_pk_mul_f32 v[24:25], v[12:13], v[20:21] op_sel_hi:[1,0]
	v_pk_mul_f32 v[6:7], v[14:15], v[6:7]
	v_exp_f32_e32 v12, v24
	v_exp_f32_e32 v13, v25
	v_pk_mul_f32 v[14:15], v[14:15], v[20:21] op_sel_hi:[1,0]
	v_exp_f32_e32 v18, v18
	v_exp_f32_e32 v19, v19
	v_exp_f32_e32 v14, v14
	v_exp_f32_e32 v15, v15
	v_pk_add_f32 v[16:17], v[16:17], 1.0 op_sel_hi:[1,0]
	v_pk_add_f32 v[12:13], v[12:13], 1.0 op_sel_hi:[1,0]
	v_rcp_f32_e32 v16, v16
	v_rcp_f32_e32 v17, v17
	v_rcp_f32_e32 v12, v12
	v_rcp_f32_e32 v13, v13
	v_mul_f32_e32 v22, v147, v147
	v_pk_add_f32 v[18:19], v[18:19], 1.0 op_sel_hi:[1,0]
	v_pk_add_f32 v[14:15], v[14:15], 1.0 op_sel_hi:[1,0]
	v_pk_mul_f32 v[8:9], v[8:9], v[22:23] op_sel_hi:[1,0]
	v_rcp_f32_e32 v18, v18
	v_rcp_f32_e32 v19, v19
	v_rcp_f32_e32 v14, v14
	v_rcp_f32_e32 v15, v15
	v_pk_mul_f32 v[4:5], v[4:5], v[22:23] op_sel_hi:[1,0]
	v_pk_mul_f32 v[8:9], v[8:9], v[16:17]
	v_pk_mul_f32 v[12:13], v[4:5], v[12:13]
	v_cvt_pk_bf16_f32 v4, v8, v9
	v_mad_i64_i32 v[8:9], s[34:35], v145, s11, v[116:117]
	v_pk_mul_f32 v[10:11], v[10:11], v[22:23] op_sel_hi:[1,0]
	v_pk_mul_f32 v[6:7], v[6:7], v[22:23] op_sel_hi:[1,0]
	v_lshl_add_u64 v[8:9], v[8:9], 0, v[118:119]
	s_andn2_b64 vcc, exec, s[38:39]
	s_mov_b64 s[34:35], -1
	v_pk_mul_f32 v[10:11], v[10:11], v[18:19]
	v_pk_mul_f32 v[14:15], v[6:7], v[14:15]
	v_cvt_pk_bf16_f32 v5, v10, v11
	v_cvt_pk_bf16_f32 v6, v12, v13
	s_nop 0
	v_cvt_pk_bf16_f32 v7, v14, v15
	global_store_dwordx4 v[8:9], v[4:7], off
	s_cbranch_vccnz .LBB0_165
	s_andn2_b64 vcc, exec, s[26:27]
	s_cbranch_vccnz .LBB0_164
	s_barrier
	s_branch .LBB0_164

.LBB0_559:
	s_add_i32 vcc_lo, s34, 2
	s_add_u32 s35, s42, 0x80
	s_addc_u32 s52, s43, 0
	s_add_i32 s53, 0, 0x10000
	s_cmp_eq_u32 s77, s34
	s_cselect_b32 s57, s51, s52
	s_cselect_b32 s56, s50, s35
	s_cselect_b32 s35, s36, s97
	s_cselect_b32 s34, s37, s49
	s_add_i32 s68, 0, 0x14000
	v_add_u32_e32 v136, s53, v200
	v_add_u32_e32 v186, s68, v200
	ds_read_b128 v[116:119], v136
	ds_read_b128 v[120:123], v136 offset:1024
	ds_read_b128 v[124:127], v136 offset:2048
	ds_read_b128 v[136:139], v136 offset:3072
	ds_read_b128 v[148:151], v186
	ds_read_b128 v[152:155], v186 offset:1024
	ds_read_b128 v[182:185], v186 offset:2048
	ds_read_b128 v[186:189], v186 offset:3072
	v_lshl_add_u64 v[198:199], s[42:43], 0, v[178:179]
	s_add_i32 m0, s59, 0xc000
	ds_read_b128 v[190:193], v202
	ds_read_b128 v[194:197], v202 offset:1024
	ds_read_b128 v[204:207], v202 offset:2048
	ds_read_b128 v[208:211], v202 offset:3072
	ds_read_b128 v[212:215], v202 offset:4096
	ds_read_b128 v[216:219], v202 offset:5120
	ds_read_b128 v[228:231], v202 offset:6144
	ds_read_b128 v[232:235], v202 offset:7168
	global_load_lds_dwordx4 v[198:199], off
	v_lshl_add_u64 v[198:199], s[42:43], 0, v[180:181]
	s_add_i32 m0, s59, 0xe000
	s_nop 0
	global_load_lds_dwordx4 v[198:199], off
	s_waitcnt vmcnt(8)
	s_waitcnt lgkmcnt(0)
	s_barrier
	s_setprio 1
	v_mfma_f32_16x16x32_bf16 v[144:147], v[116:119], v[190:193], v[144:147]
	v_mfma_f32_16x16x32_bf16 v[144:147], v[120:123], v[194:197], v[144:147]
	v_mfma_f32_16x16x32_bf16 v[140:143], v[124:127], v[190:193], v[140:143]
	v_mfma_f32_16x16x32_bf16 v[140:143], v[136:139], v[194:197], v[140:143]
	v_mfma_f32_16x16x32_bf16 v[108:111], v[124:127], v[204:207], v[108:111]
	v_mfma_f32_16x16x32_bf16 v[108:111], v[136:139], v[208:211], v[108:111]
	v_mfma_f32_16x16x32_bf16 v[112:115], v[116:119], v[204:207], v[112:115]
	v_mfma_f32_16x16x32_bf16 v[112:115], v[120:123], v[208:211], v[112:115]
	v_mfma_f32_16x16x32_bf16 v[96:99], v[116:119], v[212:215], v[96:99]
	v_mfma_f32_16x16x32_bf16 v[96:99], v[120:123], v[216:219], v[96:99]
	v_mfma_f32_16x16x32_bf16 v[92:95], v[124:127], v[212:215], v[92:95]
	v_mfma_f32_16x16x32_bf16 v[92:95], v[136:139], v[216:219], v[92:95]
	v_mfma_f32_16x16x32_bf16 v[76:79], v[124:127], v[228:231], v[76:79]
	v_mfma_f32_16x16x32_bf16 v[76:79], v[136:139], v[232:235], v[76:79]
	v_mfma_f32_16x16x32_bf16 v[80:83], v[116:119], v[228:231], v[80:83]
	v_mfma_f32_16x16x32_bf16 v[80:83], v[120:123], v[232:235], v[80:83]
	v_mfma_f32_16x16x32_bf16 v[132:135], v[148:151], v[190:193], v[132:135]
	v_mfma_f32_16x16x32_bf16 v[132:135], v[152:155], v[194:197], v[132:135]
	v_mfma_f32_16x16x32_bf16 v[128:131], v[182:185], v[190:193], v[128:131]
	v_mfma_f32_16x16x32_bf16 v[128:131], v[186:189], v[194:197], v[128:131]
	v_mfma_f32_16x16x32_bf16 v[100:103], v[182:185], v[204:207], v[100:103]
	v_mfma_f32_16x16x32_bf16 v[100:103], v[186:189], v[208:211], v[100:103]
	v_mfma_f32_16x16x32_bf16 v[104:107], v[148:151], v[204:207], v[104:107]
	v_mfma_f32_16x16x32_bf16 v[104:107], v[152:155], v[208:211], v[104:107]
	v_mfma_f32_16x16x32_bf16 v[88:91], v[148:151], v[212:215], v[88:91]
	v_mfma_f32_16x16x32_bf16 v[88:91], v[152:155], v[216:219], v[88:91]
	v_mfma_f32_16x16x32_bf16 v[84:87], v[182:185], v[212:215], v[84:87]
	v_mfma_f32_16x16x32_bf16 v[84:87], v[186:189], v[216:219], v[84:87]
	v_mfma_f32_16x16x32_bf16 v[68:71], v[182:185], v[228:231], v[68:71]
	v_mfma_f32_16x16x32_bf16 v[68:71], v[186:189], v[232:235], v[68:71]
	v_mfma_f32_16x16x32_bf16 v[72:75], v[148:151], v[228:231], v[72:75]
	v_mfma_f32_16x16x32_bf16 v[72:75], v[152:155], v[232:235], v[72:75]
	s_setprio 0
	s_barrier
	s_add_i32 s52, s53, s58
	v_lshl_add_u64 v[198:199], s[34:35], 0, v[174:175]
	s_mov_b32 m0, s52
	ds_read_b128 v[190:193], v202 offset:16384
	ds_read_b128 v[194:197], v202 offset:17408
	ds_read_b128 v[204:207], v202 offset:18432
	ds_read_b128 v[208:211], v202 offset:19456
	ds_read_b128 v[212:215], v202 offset:20480
	ds_read_b128 v[216:219], v202 offset:21504
	ds_read_b128 v[228:231], v202 offset:22528
	ds_read_b128 v[232:235], v202 offset:23552
	global_load_lds_dwordx4 v[198:199], off
	s_add_i32 m0, s52, 0x2000
	s_add_u32 s52, s34, 0x4000
	v_lshl_add_u64 v[198:199], s[34:35], 0, v[0:1]
	s_addc_u32 s53, s35, 0
	s_add_i32 s68, s68, s58
	global_load_lds_dwordx4 v[198:199], off
	v_lshl_add_u64 v[198:199], s[52:53], 0, v[174:175]
	s_mov_b32 m0, s68
	v_lshl_add_u64 v[236:237], s[56:57], 0, v[172:173]
	global_load_lds_dwordx4 v[198:199], off
	v_lshl_add_u64 v[198:199], s[52:53], 0, v[0:1]
	s_add_i32 m0, s68, 0x2000
	s_nop 0
	global_load_lds_dwordx4 v[198:199], off
	v_lshl_add_u64 v[198:199], s[56:57], 0, v[176:177]
	s_mov_b32 m0, s59
	s_nop 0
	global_load_lds_dwordx4 v[198:199], off
	s_mov_b32 m0, s60
	s_nop 0
	global_load_lds_dwordx4 v[236:237], off
	s_waitcnt vmcnt(8)
	s_waitcnt lgkmcnt(0)
	s_barrier
	s_setprio 1
	v_mfma_f32_16x16x32_bf16 v[64:67], v[116:119], v[190:193], v[64:67]
	v_mfma_f32_16x16x32_bf16 v[64:67], v[120:123], v[194:197], v[64:67]
	v_mfma_f32_16x16x32_bf16 v[60:63], v[124:127], v[190:193], v[60:63]
	v_mfma_f32_16x16x32_bf16 v[60:63], v[136:139], v[194:197], v[60:63]
	v_mfma_f32_16x16x32_bf16 v[44:47], v[124:127], v[204:207], v[44:47]
	v_mfma_f32_16x16x32_bf16 v[44:47], v[136:139], v[208:211], v[44:47]
	v_mfma_f32_16x16x32_bf16 v[48:51], v[116:119], v[204:207], v[48:51]
	v_mfma_f32_16x16x32_bf16 v[48:51], v[120:123], v[208:211], v[48:51]
	v_mfma_f32_16x16x32_bf16 v[32:35], v[116:119], v[212:215], v[32:35]
	v_mfma_f32_16x16x32_bf16 v[32:35], v[120:123], v[216:219], v[32:35]
	v_mfma_f32_16x16x32_bf16 v[28:31], v[124:127], v[212:215], v[28:31]
	v_mfma_f32_16x16x32_bf16 v[28:31], v[136:139], v[216:219], v[28:31]
	v_mfma_f32_16x16x32_bf16 v[12:15], v[124:127], v[228:231], v[12:15]
	v_mfma_f32_16x16x32_bf16 v[12:15], v[136:139], v[232:235], v[12:15]
	v_mfma_f32_16x16x32_bf16 v[16:19], v[116:119], v[228:231], v[16:19]
	v_mfma_f32_16x16x32_bf16 v[16:19], v[120:123], v[232:235], v[16:19]
	v_mfma_f32_16x16x32_bf16 v[56:59], v[148:151], v[190:193], v[56:59]
	v_mfma_f32_16x16x32_bf16 v[56:59], v[152:155], v[194:197], v[56:59]
	v_mfma_f32_16x16x32_bf16 v[52:55], v[182:185], v[190:193], v[52:55]
	v_mfma_f32_16x16x32_bf16 v[52:55], v[186:189], v[194:197], v[52:55]
	v_mfma_f32_16x16x32_bf16 v[36:39], v[182:185], v[204:207], v[36:39]
	v_mfma_f32_16x16x32_bf16 v[36:39], v[186:189], v[208:211], v[36:39]
	v_mfma_f32_16x16x32_bf16 v[40:43], v[148:151], v[204:207], v[40:43]
	v_mfma_f32_16x16x32_bf16 v[40:43], v[152:155], v[208:211], v[40:43]
	v_mfma_f32_16x16x32_bf16 v[24:27], v[148:151], v[212:215], v[24:27]
	v_mfma_f32_16x16x32_bf16 v[24:27], v[152:155], v[216:219], v[24:27]
	v_mfma_f32_16x16x32_bf16 v[20:23], v[182:185], v[212:215], v[20:23]
	v_mfma_f32_16x16x32_bf16 v[20:23], v[186:189], v[216:219], v[20:23]
	v_mfma_f32_16x16x32_bf16 v[4:7], v[182:185], v[228:231], v[4:7]
	v_mfma_f32_16x16x32_bf16 v[4:7], v[186:189], v[232:235], v[4:7]
	v_mfma_f32_16x16x32_bf16 v[8:11], v[148:151], v[228:231], v[8:11]
	v_mfma_f32_16x16x32_bf16 v[8:11], v[152:155], v[232:235], v[8:11]
	s_setprio 0
	s_barrier
	s_add_i32 s68, 0, 0x18000
	s_add_i32 vcc_hi, 0, 0x1c000
	v_add_u32_e32 v136, s68, v200
	v_add_u32_e32 v186, vcc_hi, v200
	ds_read_b128 v[116:119], v136
	ds_read_b128 v[120:123], v136 offset:1024
	ds_read_b128 v[124:127], v136 offset:2048
	ds_read_b128 v[136:139], v136 offset:3072
	ds_read_b128 v[148:151], v186
	ds_read_b128 v[152:155], v186 offset:1024
	ds_read_b128 v[182:185], v186 offset:2048
	ds_read_b128 v[186:189], v186 offset:3072
	s_add_u32 s52, s56, s26
	s_addc_u32 s53, s57, 0
	s_mov_b32 m0, s61
	v_lshl_add_u64 v[238:239], s[52:53], 0, v[176:177]
	ds_read_b128 v[190:193], v202 offset:32768
	ds_read_b128 v[194:197], v202 offset:33792
	ds_read_b128 v[204:207], v202 offset:34816
	ds_read_b128 v[208:211], v202 offset:35840
	ds_read_b128 v[212:215], v202 offset:36864
	ds_read_b128 v[216:219], v202 offset:37888
	ds_read_b128 v[228:231], v202 offset:38912
	ds_read_b128 v[232:235], v202 offset:39936
	global_load_lds_dwordx4 v[238:239], off
	v_lshl_add_u64 v[238:239], s[52:53], 0, v[172:173]
	s_mov_b32 m0, s62
	s_nop 0
	global_load_lds_dwordx4 v[238:239], off
	s_waitcnt vmcnt(8)
	s_waitcnt lgkmcnt(0)
	s_barrier
	s_setprio 1
	v_mfma_f32_16x16x32_bf16 v[144:147], v[116:119], v[190:193], v[144:147]
	v_mfma_f32_16x16x32_bf16 v[144:147], v[120:123], v[194:197], v[144:147]
	v_mfma_f32_16x16x32_bf16 v[140:143], v[124:127], v[190:193], v[140:143]
	v_mfma_f32_16x16x32_bf16 v[140:143], v[136:139], v[194:197], v[140:143]
	v_mfma_f32_16x16x32_bf16 v[108:111], v[124:127], v[204:207], v[108:111]
	v_mfma_f32_16x16x32_bf16 v[108:111], v[136:139], v[208:211], v[108:111]
	v_mfma_f32_16x16x32_bf16 v[112:115], v[116:119], v[204:207], v[112:115]
	v_mfma_f32_16x16x32_bf16 v[112:115], v[120:123], v[208:211], v[112:115]
	v_mfma_f32_16x16x32_bf16 v[96:99], v[116:119], v[212:215], v[96:99]
	v_mfma_f32_16x16x32_bf16 v[96:99], v[120:123], v[216:219], v[96:99]
	v_mfma_f32_16x16x32_bf16 v[92:95], v[124:127], v[212:215], v[92:95]
	v_mfma_f32_16x16x32_bf16 v[92:95], v[136:139], v[216:219], v[92:95]
	v_mfma_f32_16x16x32_bf16 v[76:79], v[124:127], v[228:231], v[76:79]
	v_mfma_f32_16x16x32_bf16 v[76:79], v[136:139], v[232:235], v[76:79]
	v_mfma_f32_16x16x32_bf16 v[80:83], v[116:119], v[228:231], v[80:83]
	v_mfma_f32_16x16x32_bf16 v[80:83], v[120:123], v[232:235], v[80:83]
	v_mfma_f32_16x16x32_bf16 v[132:135], v[148:151], v[190:193], v[132:135]
	v_mfma_f32_16x16x32_bf16 v[132:135], v[152:155], v[194:197], v[132:135]
	v_mfma_f32_16x16x32_bf16 v[128:131], v[182:185], v[190:193], v[128:131]
	v_mfma_f32_16x16x32_bf16 v[128:131], v[186:189], v[194:197], v[128:131]
	v_mfma_f32_16x16x32_bf16 v[100:103], v[182:185], v[204:207], v[100:103]
	v_mfma_f32_16x16x32_bf16 v[100:103], v[186:189], v[208:211], v[100:103]
	v_mfma_f32_16x16x32_bf16 v[104:107], v[148:151], v[204:207], v[104:107]
	v_mfma_f32_16x16x32_bf16 v[104:107], v[152:155], v[208:211], v[104:107]
	v_mfma_f32_16x16x32_bf16 v[88:91], v[148:151], v[212:215], v[88:91]
	v_mfma_f32_16x16x32_bf16 v[88:91], v[152:155], v[216:219], v[88:91]
	v_mfma_f32_16x16x32_bf16 v[84:87], v[182:185], v[212:215], v[84:87]
	v_mfma_f32_16x16x32_bf16 v[84:87], v[186:189], v[216:219], v[84:87]
	v_mfma_f32_16x16x32_bf16 v[68:71], v[182:185], v[228:231], v[68:71]
	v_mfma_f32_16x16x32_bf16 v[68:71], v[186:189], v[232:235], v[68:71]
	v_mfma_f32_16x16x32_bf16 v[72:75], v[148:151], v[228:231], v[72:75]
	v_mfma_f32_16x16x32_bf16 v[72:75], v[152:155], v[232:235], v[72:75]
	s_setprio 0
	s_barrier
	s_add_u32 s52, s34, 0x40000
	s_addc_u32 s53, s35, 0
	s_add_i32 s56, s68, s58
	v_lshl_add_u64 v[238:239], s[52:53], 0, v[174:175]
	s_mov_b32 m0, s56
	ds_read_b128 v[190:193], v202 offset:49152
	ds_read_b128 v[194:197], v202 offset:50176
	ds_read_b128 v[204:207], v202 offset:51200
	ds_read_b128 v[208:211], v202 offset:52224
	ds_read_b128 v[212:215], v202 offset:53248
	ds_read_b128 v[216:219], v202 offset:54272
	ds_read_b128 v[228:231], v202 offset:55296
	ds_read_b128 v[232:235], v202 offset:56320
	global_load_lds_dwordx4 v[238:239], off
	s_add_i32 m0, s56, 0x2000
	s_add_u32 s34, s34, 0x44000
	v_lshl_add_u64 v[238:239], s[52:53], 0, v[0:1]
	s_addc_u32 s35, s35, 0
	s_add_i32 s52, vcc_hi, s58
	global_load_lds_dwordx4 v[238:239], off
	v_lshl_add_u64 v[238:239], s[34:35], 0, v[174:175]
	s_mov_b32 m0, s52
	v_lshl_add_u64 v[198:199], v[198:199], 0, s[14:15]
	global_load_lds_dwordx4 v[238:239], off
	v_lshl_add_u64 v[238:239], s[34:35], 0, v[0:1]
	s_add_i32 m0, s52, 0x2000
	s_nop 0
	global_load_lds_dwordx4 v[238:239], off
	s_mov_b32 m0, s71
	s_nop 0
	global_load_lds_dwordx4 v[198:199], off
	v_lshl_add_u64 v[198:199], v[236:237], 0, s[14:15]
	s_mov_b32 m0, s76
	s_nop 0
	global_load_lds_dwordx4 v[198:199], off
	s_waitcnt vmcnt(8)
	s_waitcnt lgkmcnt(0)
	s_barrier
	s_setprio 1
	v_mfma_f32_16x16x32_bf16 v[64:67], v[116:119], v[190:193], v[64:67]
	v_mfma_f32_16x16x32_bf16 v[64:67], v[120:123], v[194:197], v[64:67]
	v_mfma_f32_16x16x32_bf16 v[60:63], v[124:127], v[190:193], v[60:63]
	v_mfma_f32_16x16x32_bf16 v[60:63], v[136:139], v[194:197], v[60:63]
	v_mfma_f32_16x16x32_bf16 v[44:47], v[124:127], v[204:207], v[44:47]
	v_mfma_f32_16x16x32_bf16 v[44:47], v[136:139], v[208:211], v[44:47]
	v_mfma_f32_16x16x32_bf16 v[48:51], v[116:119], v[204:207], v[48:51]
	v_mfma_f32_16x16x32_bf16 v[48:51], v[120:123], v[208:211], v[48:51]
	v_mfma_f32_16x16x32_bf16 v[32:35], v[116:119], v[212:215], v[32:35]
	v_mfma_f32_16x16x32_bf16 v[32:35], v[120:123], v[216:219], v[32:35]
	v_mfma_f32_16x16x32_bf16 v[28:31], v[124:127], v[212:215], v[28:31]
	v_mfma_f32_16x16x32_bf16 v[28:31], v[136:139], v[216:219], v[28:31]
	v_mfma_f32_16x16x32_bf16 v[12:15], v[124:127], v[228:231], v[12:15]
	v_mfma_f32_16x16x32_bf16 v[12:15], v[136:139], v[232:235], v[12:15]
	v_mfma_f32_16x16x32_bf16 v[16:19], v[116:119], v[228:231], v[16:19]
	v_mfma_f32_16x16x32_bf16 v[16:19], v[120:123], v[232:235], v[16:19]
	v_mfma_f32_16x16x32_bf16 v[56:59], v[148:151], v[190:193], v[56:59]
	v_mfma_f32_16x16x32_bf16 v[56:59], v[152:155], v[194:197], v[56:59]
	v_mfma_f32_16x16x32_bf16 v[52:55], v[182:185], v[190:193], v[52:55]
	v_mfma_f32_16x16x32_bf16 v[52:55], v[186:189], v[194:197], v[52:55]
	v_mfma_f32_16x16x32_bf16 v[36:39], v[182:185], v[204:207], v[36:39]
	v_mfma_f32_16x16x32_bf16 v[36:39], v[186:189], v[208:211], v[36:39]
	v_mfma_f32_16x16x32_bf16 v[40:43], v[148:151], v[204:207], v[40:43]
	v_mfma_f32_16x16x32_bf16 v[40:43], v[152:155], v[208:211], v[40:43]
	v_mfma_f32_16x16x32_bf16 v[24:27], v[148:151], v[212:215], v[24:27]
	v_mfma_f32_16x16x32_bf16 v[24:27], v[152:155], v[216:219], v[24:27]
	v_mfma_f32_16x16x32_bf16 v[20:23], v[182:185], v[212:215], v[20:23]
	v_mfma_f32_16x16x32_bf16 v[20:23], v[186:189], v[216:219], v[20:23]
	v_mfma_f32_16x16x32_bf16 v[4:7], v[182:185], v[228:231], v[4:7]
	v_mfma_f32_16x16x32_bf16 v[4:7], v[186:189], v[232:235], v[4:7]
	v_mfma_f32_16x16x32_bf16 v[8:11], v[148:151], v[228:231], v[8:11]
	v_mfma_f32_16x16x32_bf16 v[8:11], v[152:155], v[232:235], v[8:11]
	s_setprio 0
	s_barrier
	s_add_u32 s49, s49, 0x80000
	s_addc_u32 s97, s97, 0
	s_add_u32 s42, s42, 0x100
	s_addc_u32 s43, s43, 0
	s_cmp_ge_u32 vcc_lo, s69
	s_mov_b32 s34, vcc_lo
	s_cbranch_scc0 .LBB0_559
	s_and_b64 vcc, exec, s[46:47]
	s_cbranch_vccz .LBB0_562
	s_nop 0
.LBB0_562:
	v_lshl_or_b32 v182, s64, 8, v201
	v_lshl_add_u32 v186, s96, 8, v3
	v_ashrrev_i32_e32 v183, 31, v182
	v_lshlrev_b64 v[212:213], 1, v[182:183]
	v_ashrrev_i32_e32 v187, 31, v186
	v_lshl_add_u64 v[184:185], s[20:21], 0, v[212:213]
	v_lshlrev_b64 v[214:215], 12, v[186:187]
	v_lshl_add_u64 v[116:117], v[184:185], 0, v[214:215]
	global_load_dwordx4 v[204:207], v[116:117], off
	global_load_dwordx4 v[208:211], v[116:117], off offset:256
	v_or_b32_e32 v196, 16, v186
	v_ashrrev_i32_e32 v197, 31, v196
	v_or_b32_e32 v192, 32, v186
	v_lshlrev_b64 v[198:199], 12, v[196:197]
	v_ashrrev_i32_e32 v193, 31, v192
	v_or_b32_e32 v188, 48, v186
	v_lshl_add_u64 v[116:117], v[184:185], 0, v[198:199]
	v_lshlrev_b64 v[194:195], 12, v[192:193]
	v_ashrrev_i32_e32 v189, 31, v188
	global_load_dwordx4 v[152:155], v[116:117], off
	global_load_dwordx4 v[148:151], v[116:117], off offset:256
	v_lshl_add_u64 v[116:117], v[184:185], 0, v[194:195]
	v_lshlrev_b64 v[190:191], 12, v[188:189]
	global_load_dwordx4 v[136:139], v[116:117], off
	global_load_dwordx4 v[124:127], v[116:117], off offset:256
	v_lshl_add_u64 v[116:117], v[184:185], 0, v[190:191]
	global_load_dwordx4 v[120:123], v[116:117], off
	s_nop 0
	global_load_dwordx4 v[116:119], v[116:117], off offset:256
	s_and_b64 vcc, exec, s[46:47]
	s_cbranch_vccz .Lmidbar_3
	s_barrier
.Lmidbar_3:
	v_lshl_add_u64 v[214:215], s[20:21], 0, v[214:215]
	v_lshl_add_u64 v[212:213], v[214:215], 0, v[212:213]
	s_lshl_b32 s42, s64, 2
	s_ashr_i32 s43, s42, 31
	s_waitcnt vmcnt(0)
	v_lshlrev_b32_e32 v216, 16, v204
	v_and_b32_e32 v217, 0xffff0000, v204
	v_lshlrev_b32_e32 v204, 16, v205
	v_and_b32_e32 v205, 0xffff0000, v205
	v_lshlrev_b32_e32 v218, 16, v206
	v_and_b32_e32 v219, 0xffff0000, v206
	v_lshlrev_b32_e32 v206, 16, v207
	v_and_b32_e32 v207, 0xffff0000, v207
	v_pk_fma_f32 v[146:147], s[44:45], v[146:147], v[204:205]
	v_pk_fma_f32 v[144:145], s[0:1], v[144:145], v[216:217]
	v_pk_fma_f32 v[204:205], s[44:45], v[142:143], v[206:207]
	v_pk_fma_f32 v[206:207], s[0:1], v[140:141], v[218:219]
	v_cvt_pk_bf16_f32 v140, v144, v145
	v_cvt_pk_bf16_f32 v141, v146, v147
	s_nop 0
	v_cvt_pk_bf16_f32 v142, v206, v207
	v_cvt_pk_bf16_f32 v143, v204, v205
	global_store_dwordx4 v[212:213], v[140:143], off
	s_nop 1
	v_mul_f32_e32 v140, v145, v145
	v_mul_f32_e32 v141, v147, v147
	v_fmac_f32_e32 v140, v144, v144
	v_fmac_f32_e32 v141, v146, v146
	v_add_f32_e32 v140, v140, v141
	v_mul_f32_e32 v141, v207, v207
	v_fmac_f32_e32 v141, v206, v206
	v_add_f32_e32 v140, v141, v140
	v_mul_f32_e32 v141, v205, v205
	v_fmac_f32_e32 v141, v204, v204
	v_add_f32_e32 v203, v141, v140
	v_lshlrev_b32_e32 v140, 16, v208
	v_and_b32_e32 v141, 0xffff0000, v208
	v_lshlrev_b32_e32 v142, 16, v209
	v_and_b32_e32 v143, 0xffff0000, v209
	v_lshlrev_b32_e32 v144, 16, v210
	v_and_b32_e32 v145, 0xffff0000, v210
	v_lshlrev_b32_e32 v146, 16, v211
	v_and_b32_e32 v147, 0xffff0000, v211
	v_pk_fma_f32 v[134:135], s[44:45], v[134:135], v[142:143]
	v_pk_fma_f32 v[132:133], s[0:1], v[132:133], v[140:141]
	v_pk_fma_f32 v[142:143], s[0:1], v[128:129], v[144:145]
	v_cvt_pk_bf16_f32 v128, v132, v133
	v_cvt_pk_bf16_f32 v129, v134, v135
	v_pk_fma_f32 v[140:141], s[44:45], v[130:131], v[146:147]
	v_cvt_pk_bf16_f32 v130, v142, v143
	s_nop 0
	v_cvt_pk_bf16_f32 v131, v140, v141
	global_store_dwordx4 v[212:213], v[128:131], off offset:256
	s_nop 1
	v_mul_f32_e32 v128, v133, v133
	v_mul_f32_e32 v129, v135, v135
	v_fmac_f32_e32 v128, v132, v132
	v_fmac_f32_e32 v129, v134, v134
	v_add_f32_e32 v128, v128, v129
	v_mul_f32_e32 v129, v143, v143
	v_fmac_f32_e32 v129, v142, v142
	v_add_f32_e32 v128, v129, v128
	v_mul_f32_e32 v129, v141, v141
	v_fmac_f32_e32 v129, v140, v140
	v_add_f32_e32 v128, v129, v128
	v_and_b32_e32 v130, 64, v221
	v_add_f32_e32 v129, v203, v128
	v_xor_b32_e32 v128, 16, v221
	v_add_u32_e32 v131, 64, v130
	v_cmp_lt_i32_e32 vcc, v128, v131
	s_nop 1
	v_cndmask_b32_e32 v128, v221, v128, vcc
	v_lshlrev_b32_e32 v128, 2, v128
	ds_bpermute_b32 v130, v128, v129
	s_waitcnt lgkmcnt(0)
	v_add_f32_e32 v130, v129, v130
	v_xor_b32_e32 v129, 32, v221
	v_cmp_lt_i32_e32 vcc, v129, v131
	s_nop 1
	v_cndmask_b32_e32 v129, v221, v129, vcc
	v_lshlrev_b32_e32 v129, 2, v129
	ds_bpermute_b32 v131, v129, v130
	s_and_saveexec_b64 s[34:35], s[38:39]
	s_cbranch_execz .LBB0_564
	v_lshlrev_b64 v[132:133], 7, v[186:187]
	v_lshl_add_u64 v[132:133], s[24:25], 0, v[132:133]
	v_lshl_add_u64 v[132:133], s[42:43], 2, v[132:133]
	s_lshl_b32 s64, s63, 2
	v_lshl_add_u64 v[132:133], v[132:133], 0, s[64:65]
	s_waitcnt lgkmcnt(0)
	v_add_f32_e32 v130, v130, v131
	global_store_dword v[132:133], v130, off
